# P5 step 3: earlier-row update runs four rows per stage with the next stage's LDS reads issued a whole stage ahead into a second register set (was two rows per trip, reads half a trip ahead)
# speedup vs baseline: 1.0043x; 1.0043x over previous
; __device__ __forceinline__ float bf2f(unsigned short b) { return __uint_as_float((unsigned)b << 16); }
; __device__ __forceinline__ void prep_unit(const int PREP_STEPS, LAS unsigned char* lds, int uidx, bf16* Qg, bf16* Kg, bf16* Vg, bf16* KT, bf16* QK, const bf16* HALO, const float* wconv, const float* BETA, const float* GG, float* GC) {
;     ...
;         for (int I = 0; I < 4; ++I) {
;             float au[16], aw[16];
; #pragma unroll
;             for (int r = 0; r < 16; ++r) { au[r] = bf2f(Vs[(16 * I + r) * 136 + c]) * betas[16 * I + r]; aw[r] = bf2f(Ks[(16 * I + r) * 136 + c]) * egcs[16 * I + r]; }
;             const int l16 = lane & 15;
; #pragma unroll 2
;             for (int j = 0; j < 16 * I; ++j) {
;                 const float xu = bf2f(Vs[j * 136 + c]), xw = bf2f(Ks[j * 136 + c]);
;                 const int av = __builtin_bit_cast(int, Af[j * 68 + 16 * I + l16]);
;                 Rows16<0>::run(av, xu, xw, au, aw, -1);
;             }
.Lfs_I:
	ds_read_b128 v[40:43], v48
	ds_read_b128 v[44:47], v48 offset:16
	ds_read_u16 v20, v17
	ds_read_u16 v21, v17 offset:272
	ds_read_u16 v22, v17 offset:544
	ds_read_u16 v23, v17 offset:816
	ds_read_u16 v24, v17 offset:1088
	ds_read_u16 v25, v17 offset:1360
	ds_read_u16 v26, v17 offset:1632
	ds_read_u16 v27, v17 offset:1904
	s_waitcnt lgkmcnt(0)
	v_lshlrev_b32_e32 v20, 16, v20
	v_lshlrev_b32_e32 v21, 16, v21
	v_lshlrev_b32_e32 v22, 16, v22
	v_lshlrev_b32_e32 v23, 16, v23
	v_lshlrev_b32_e32 v24, 16, v24
	v_lshlrev_b32_e32 v25, 16, v25
	v_lshlrev_b32_e32 v26, 16, v26
	v_lshlrev_b32_e32 v27, 16, v27
	v_mul_f32_e32 v0, v20, v40
	v_mul_f32_e32 v4, v21, v41
	v_mul_f32_e32 v8, v22, v42
	v_mul_f32_e32 v12, v23, v43
	v_mul_f32_e32 v1, v24, v44
	v_mul_f32_e32 v5, v25, v45
	v_mul_f32_e32 v9, v26, v46
	v_mul_f32_e32 v13, v27, v47
	ds_read_b128 v[40:43], v48 offset:32
	ds_read_b128 v[44:47], v48 offset:48
	ds_read_u16 v20, v17 offset:2176
	ds_read_u16 v21, v17 offset:2448
	ds_read_u16 v22, v17 offset:2720
	ds_read_u16 v23, v17 offset:2992
	ds_read_u16 v24, v17 offset:3264
	ds_read_u16 v25, v17 offset:3536
	ds_read_u16 v26, v17 offset:3808
	ds_read_u16 v27, v17 offset:4080
	s_waitcnt lgkmcnt(0)
	v_lshlrev_b32_e32 v20, 16, v20
	v_lshlrev_b32_e32 v21, 16, v21
	v_lshlrev_b32_e32 v22, 16, v22
	v_lshlrev_b32_e32 v23, 16, v23
	v_lshlrev_b32_e32 v24, 16, v24
	v_lshlrev_b32_e32 v25, 16, v25
	v_lshlrev_b32_e32 v26, 16, v26
	v_lshlrev_b32_e32 v27, 16, v27
	v_mul_f32_e32 v2, v20, v40
	v_mul_f32_e32 v6, v21, v41
	v_mul_f32_e32 v10, v22, v42
	v_mul_f32_e32 v14, v23, v43
	v_mul_f32_e32 v3, v24, v44
	v_mul_f32_e32 v7, v25, v45
	v_mul_f32_e32 v11, v26, v46
	v_mul_f32_e32 v15, v27, v47
	s_cmp_eq_u32 s1, 0
	s_cbranch_scc1 .Lfs_q
	s_lshl_b32 s0, s1, 1
	s_lshl_b32 s14, s1, 6
	v_mov_b32_e32 v18, v16
	v_add_u32_e32 v19, s14, v49
	ds_read_u16 v36, v18
	ds_read_b128 v[40:43], v19
	ds_read_u16 v37, v18 offset:272
	ds_read_b128 v[44:47], v19 offset:272
	ds_read_u16 v166, v18 offset:544
	ds_read_b128 v[168:171], v19 offset:544
	ds_read_u16 v167, v18 offset:816
	ds_read_b128 v[172:175], v19 offset:816
.Lfs_j:
	ds_read_u16 v176, v18 offset:1088
	ds_read_b128 v[180:183], v19 offset:1088
	ds_read_u16 v177, v18 offset:1360
	ds_read_b128 v[184:187], v19 offset:1360
	ds_read_u16 v178, v18 offset:1632
	ds_read_b128 v[188:191], v19 offset:1632
	ds_read_u16 v179, v18 offset:1904
	ds_read_b128 v[192:195], v19 offset:1904
	s_waitcnt lgkmcnt(8)
	v_lshlrev_b32_e32 v38, 16, v36
	v_lshlrev_b32_e32 v39, 16, v37
	v_lshlrev_b32_e32 v196, 16, v166
	v_lshlrev_b32_e32 v197, 16, v167
	s_nop 1
	v_mfma_f32_4x4x1_16b_f32 v[0:3], v40, v38, v[0:3]
	v_mfma_f32_4x4x1_16b_f32 v[4:7], v41, v38, v[4:7]
	v_mfma_f32_4x4x1_16b_f32 v[8:11], v42, v38, v[8:11]
	v_mfma_f32_4x4x1_16b_f32 v[12:15], v43, v38, v[12:15]
	v_mfma_f32_4x4x1_16b_f32 v[0:3], v44, v39, v[0:3]
	v_mfma_f32_4x4x1_16b_f32 v[4:7], v45, v39, v[4:7]
	v_mfma_f32_4x4x1_16b_f32 v[8:11], v46, v39, v[8:11]
	v_mfma_f32_4x4x1_16b_f32 v[12:15], v47, v39, v[12:15]
	v_mfma_f32_4x4x1_16b_f32 v[0:3], v168, v196, v[0:3]
	v_mfma_f32_4x4x1_16b_f32 v[4:7], v169, v196, v[4:7]
	v_mfma_f32_4x4x1_16b_f32 v[8:11], v170, v196, v[8:11]
	v_mfma_f32_4x4x1_16b_f32 v[12:15], v171, v196, v[12:15]
	v_mfma_f32_4x4x1_16b_f32 v[0:3], v172, v197, v[0:3]
	v_mfma_f32_4x4x1_16b_f32 v[4:7], v173, v197, v[4:7]
	v_mfma_f32_4x4x1_16b_f32 v[8:11], v174, v197, v[8:11]
	v_mfma_f32_4x4x1_16b_f32 v[12:15], v175, v197, v[12:15]
	v_add_u32_e32 v18, 0x880, v18
	v_add_u32_e32 v19, 0x880, v19
	ds_read_u16 v36, v18
	ds_read_b128 v[40:43], v19
	ds_read_u16 v37, v18 offset:272
	ds_read_b128 v[44:47], v19 offset:272
	ds_read_u16 v166, v18 offset:544
	ds_read_b128 v[168:171], v19 offset:544
	ds_read_u16 v167, v18 offset:816
	ds_read_b128 v[172:175], v19 offset:816
	s_waitcnt lgkmcnt(8)
	v_lshlrev_b32_e32 v38, 16, v176
	v_lshlrev_b32_e32 v39, 16, v177
	v_lshlrev_b32_e32 v196, 16, v178
	v_lshlrev_b32_e32 v197, 16, v179
	s_nop 1
	v_mfma_f32_4x4x1_16b_f32 v[0:3], v180, v38, v[0:3]
	v_mfma_f32_4x4x1_16b_f32 v[4:7], v181, v38, v[4:7]
	v_mfma_f32_4x4x1_16b_f32 v[8:11], v182, v38, v[8:11]
	v_mfma_f32_4x4x1_16b_f32 v[12:15], v183, v38, v[12:15]
	v_mfma_f32_4x4x1_16b_f32 v[0:3], v184, v39, v[0:3]
	v_mfma_f32_4x4x1_16b_f32 v[4:7], v185, v39, v[4:7]
	v_mfma_f32_4x4x1_16b_f32 v[8:11], v186, v39, v[8:11]
	v_mfma_f32_4x4x1_16b_f32 v[12:15], v187, v39, v[12:15]
	v_mfma_f32_4x4x1_16b_f32 v[0:3], v188, v196, v[0:3]
	v_mfma_f32_4x4x1_16b_f32 v[4:7], v189, v196, v[4:7]
	v_mfma_f32_4x4x1_16b_f32 v[8:11], v190, v196, v[8:11]
	v_mfma_f32_4x4x1_16b_f32 v[12:15], v191, v196, v[12:15]
	v_mfma_f32_4x4x1_16b_f32 v[0:3], v192, v197, v[0:3]
	v_mfma_f32_4x4x1_16b_f32 v[4:7], v193, v197, v[4:7]
	v_mfma_f32_4x4x1_16b_f32 v[8:11], v194, v197, v[8:11]
	v_mfma_f32_4x4x1_16b_f32 v[12:15], v195, v197, v[12:15]
	s_sub_i32 s0, s0, 1
	s_cmp_lg_u32 s0, 0
	s_cbranch_scc1 .Lfs_j
	s_waitcnt lgkmcnt(0)
	s_nop 4
